# grid barrier: non-leader CUs invalidate L1 before polling the release flag instead of after
# speedup vs baseline: 1.0042x; 1.0023x over previous
; __device__ __forceinline__ unsigned xb_ld(unsigned* p)              { return __hip_atomic_load(p, __ATOMIC_RELAXED, __HIP_MEMORY_SCOPE_AGENT); }
; __device__ __forceinline__ unsigned xb_add(unsigned* p, unsigned v) { return __hip_atomic_fetch_add(p, v, __ATOMIC_RELAXED, __HIP_MEMORY_SCOPE_AGENT); }
; #define XB_SPIN(cond, bar) do { unsigned _sp = 0; while (cond) { __builtin_amdgcn_s_sleep(1); \
;     if ((++_sp & 255u) == 0u) { if (xb_ld(&(bar)[XB_TMO])) break; if (_sp > XB_SPIN_CAP) { atomicAdd(&(bar)[XB_TMO], 1u); break; } } } } while (0)
; __device__ __forceinline__ void xcd_barrier(const XcdBarrier& b) {
;     ...
;         const unsigned old = xb_add(&bar[XB_XSUB(b.x)], 1u);
;         const unsigned gen = old / nloc;
;         if (old + 1u == (gen + 1u) * nloc) {
;             __builtin_amdgcn_fence(__ATOMIC_RELEASE, "agent");
;             asm volatile("s_waitcnt vmcnt(0)" ::: "memory");
;             const unsigned og = xb_add(&bar[XB_TOP], 1u);
;             const unsigned tg = og / nx;
;             if (og + 1u == (tg + 1u) * nx) xb_add(&bar[XB_TOPGEN], 1u);
;             else XB_SPIN(xb_ld(&bar[XB_TOPGEN]) == tg, bar);
;             __builtin_amdgcn_fence(__ATOMIC_ACQUIRE, "agent");
;             xb_add(&bar[XB_XGEN(b.x)], 1u);
;             asm volatile("s_waitcnt vmcnt(0)" ::: "memory");
;         } else {
;             XB_SPIN(xb_ld(&bar[XB_XGEN(b.x)]) == gen, bar);
;             __builtin_amdgcn_fence(__ATOMIC_ACQUIRE, "agent");
;             asm volatile("s_waitcnt vmcnt(0)" ::: "memory");
;         }
.LBB0_62:
	s_or_b64 exec, exec, s[10:11]
	v_cvt_f32_u32_e32 v4, v2
	s_waitcnt vmcnt(0)
	v_readfirstlane_b32 s8, v3
	s_add_u32 s6, s6, 0x2400
	s_addc_u32 s7, s7, 0
	v_rcp_iflag_f32_e32 v4, v4
	v_add_u32_e32 v5, s8, v1
	v_mul_f32_e32 v3, 0x4f7ffffe, v4
	v_cvt_u32_f32_e32 v3, v3
	v_sub_u32_e32 v4, 0, v2
	v_mul_lo_u32 v1, v4, v3
	v_mul_hi_u32 v1, v3, v1
	v_add_u32_e32 v1, v3, v1
	v_mul_hi_u32 v1, v5, v1
	v_mul_lo_u32 v3, v1, v2
	v_sub_u32_e32 v3, v5, v3
	v_add_u32_e32 v4, 1, v1
	v_cmp_ge_u32_e32 vcc, v3, v2
	s_nop 1
	v_cndmask_b32_e32 v1, v1, v4, vcc
	v_sub_u32_e32 v4, v3, v2
	v_cndmask_b32_e32 v3, v3, v4, vcc
	v_add_u32_e32 v4, 1, v1
	v_cmp_ge_u32_e32 vcc, v3, v2
	v_add_u32_e32 v3, 1, v5
	s_nop 0
	v_cndmask_b32_e32 v1, v1, v4, vcc
	v_mul_lo_u32 v4, v2, v1
	v_add_u32_e32 v2, v4, v2
	v_cmp_ne_u32_e32 vcc, v3, v2
	s_and_saveexec_b64 s[8:9], vcc
	s_xor_b64 s[8:9], exec, s[8:9]
	s_cbranch_execz .LBB0_76
	s_waitcnt lgkmcnt(0)
	v_mov_b32_e32 v0, 0
	buffer_inv sc1
	global_load_dword v2, v0, s[6:7] sc1
	s_waitcnt vmcnt(0)
	v_cmp_eq_u32_e32 vcc, v2, v1
	s_and_saveexec_b64 s[10:11], vcc
	s_cbranch_execz .LBB0_75
	s_mov_b32 s22, 1
	s_mov_b64 s[12:13], 0
	s_branch .LBB0_66

; __device__ __forceinline__ unsigned xb_ld(unsigned* p)              { return __hip_atomic_load(p, __ATOMIC_RELAXED, __HIP_MEMORY_SCOPE_AGENT); }
; #define XB_SPIN(cond, bar) do { unsigned _sp = 0; while (cond) { __builtin_amdgcn_s_sleep(1); \
;     if ((++_sp & 255u) == 0u) { if (xb_ld(&(bar)[XB_TMO])) break; if (_sp > XB_SPIN_CAP) { atomicAdd(&(bar)[XB_TMO], 1u); break; } } } } while (0)
; __device__ __forceinline__ void xcd_barrier(const XcdBarrier& b) {
;     ...
;         } else {
;             XB_SPIN(xb_ld(&bar[XB_XGEN(b.x)]) == gen, bar);
;             __builtin_amdgcn_fence(__ATOMIC_ACQUIRE, "agent");
;             asm volatile("s_waitcnt vmcnt(0)" ::: "memory");
;         }
.LBB0_75:
	s_or_b64 exec, exec, s[10:11]
	s_waitcnt vmcnt(0)
	s_waitcnt vmcnt(0)

; __device__ __forceinline__ unsigned xb_ld(unsigned* p)              { return __hip_atomic_load(p, __ATOMIC_RELAXED, __HIP_MEMORY_SCOPE_AGENT); }
; __device__ __forceinline__ unsigned xb_add(unsigned* p, unsigned v) { return __hip_atomic_fetch_add(p, v, __ATOMIC_RELAXED, __HIP_MEMORY_SCOPE_AGENT); }
; #define XB_SPIN(cond, bar) do { unsigned _sp = 0; while (cond) { __builtin_amdgcn_s_sleep(1); \
;     if ((++_sp & 255u) == 0u) { if (xb_ld(&(bar)[XB_TMO])) break; if (_sp > XB_SPIN_CAP) { atomicAdd(&(bar)[XB_TMO], 1u); break; } } } } while (0)
; __device__ __forceinline__ void xcd_barrier(const XcdBarrier& b) {
;     ...
;         const unsigned old = xb_add(&bar[XB_XSUB(b.x)], 1u);
;         const unsigned gen = old / nloc;
;         if (old + 1u == (gen + 1u) * nloc) {
;             __builtin_amdgcn_fence(__ATOMIC_RELEASE, "agent");
;             asm volatile("s_waitcnt vmcnt(0)" ::: "memory");
;             const unsigned og = xb_add(&bar[XB_TOP], 1u);
;             const unsigned tg = og / nx;
;             if (og + 1u == (tg + 1u) * nx) xb_add(&bar[XB_TOPGEN], 1u);
;             else XB_SPIN(xb_ld(&bar[XB_TOPGEN]) == tg, bar);
;             __builtin_amdgcn_fence(__ATOMIC_ACQUIRE, "agent");
;             xb_add(&bar[XB_XGEN(b.x)], 1u);
;             asm volatile("s_waitcnt vmcnt(0)" ::: "memory");
;         } else {
;             XB_SPIN(xb_ld(&bar[XB_XGEN(b.x)]) == gen, bar);
;             __builtin_amdgcn_fence(__ATOMIC_ACQUIRE, "agent");
;             asm volatile("s_waitcnt vmcnt(0)" ::: "memory");
;         }
.LBB0_130:
	s_or_b64 exec, exec, s[12:13]
	v_cvt_f32_u32_e32 v4, v2
	s_waitcnt vmcnt(0)
	v_readfirstlane_b32 s10, v3
	s_add_u32 s8, s8, 0x2400
	s_addc_u32 s9, s9, 0
	v_rcp_iflag_f32_e32 v4, v4
	v_add_u32_e32 v5, s10, v1
	v_mul_f32_e32 v3, 0x4f7ffffe, v4
	v_cvt_u32_f32_e32 v3, v3
	v_sub_u32_e32 v4, 0, v2
	v_mul_lo_u32 v1, v4, v3
	v_mul_hi_u32 v1, v3, v1
	v_add_u32_e32 v1, v3, v1
	v_mul_hi_u32 v1, v5, v1
	v_mul_lo_u32 v3, v1, v2
	v_sub_u32_e32 v3, v5, v3
	v_add_u32_e32 v4, 1, v1
	v_cmp_ge_u32_e32 vcc, v3, v2
	s_nop 1
	v_cndmask_b32_e32 v1, v1, v4, vcc
	v_sub_u32_e32 v4, v3, v2
	v_cndmask_b32_e32 v3, v3, v4, vcc
	v_add_u32_e32 v4, 1, v1
	v_cmp_ge_u32_e32 vcc, v3, v2
	v_add_u32_e32 v3, 1, v5
	s_nop 0
	v_cndmask_b32_e32 v1, v1, v4, vcc
	v_mul_lo_u32 v4, v2, v1
	v_add_u32_e32 v2, v4, v2
	v_cmp_ne_u32_e32 vcc, v3, v2
	s_and_saveexec_b64 s[10:11], vcc
	s_xor_b64 s[10:11], exec, s[10:11]
	s_cbranch_execz .LBB0_144
	s_waitcnt lgkmcnt(0)
	buffer_inv sc1
	global_load_dword v0, v197, s[8:9] sc1
	s_waitcnt vmcnt(0)
	v_cmp_eq_u32_e32 vcc, v0, v1
	s_and_saveexec_b64 s[12:13], vcc
	s_cbranch_execz .LBB0_143
	s_mov_b32 s24, 1
	s_mov_b64 s[14:15], 0
	s_branch .LBB0_134

; __device__ __forceinline__ unsigned xb_ld(unsigned* p)              { return __hip_atomic_load(p, __ATOMIC_RELAXED, __HIP_MEMORY_SCOPE_AGENT); }
; #define XB_SPIN(cond, bar) do { unsigned _sp = 0; while (cond) { __builtin_amdgcn_s_sleep(1); \
;     if ((++_sp & 255u) == 0u) { if (xb_ld(&(bar)[XB_TMO])) break; if (_sp > XB_SPIN_CAP) { atomicAdd(&(bar)[XB_TMO], 1u); break; } } } } while (0)
; __device__ __forceinline__ void xcd_barrier(const XcdBarrier& b) {
;     ...
;         } else {
;             XB_SPIN(xb_ld(&bar[XB_XGEN(b.x)]) == gen, bar);
;             __builtin_amdgcn_fence(__ATOMIC_ACQUIRE, "agent");
;             asm volatile("s_waitcnt vmcnt(0)" ::: "memory");
;         }
.LBB0_143:
	s_or_b64 exec, exec, s[12:13]
	s_waitcnt vmcnt(0)
	s_waitcnt vmcnt(0)

; __device__ __forceinline__ unsigned xb_ld(unsigned* p)              { return __hip_atomic_load(p, __ATOMIC_RELAXED, __HIP_MEMORY_SCOPE_AGENT); }
; __device__ __forceinline__ unsigned xb_add(unsigned* p, unsigned v) { return __hip_atomic_fetch_add(p, v, __ATOMIC_RELAXED, __HIP_MEMORY_SCOPE_AGENT); }
; #define XB_SPIN(cond, bar) do { unsigned _sp = 0; while (cond) { __builtin_amdgcn_s_sleep(1); \
;     if ((++_sp & 255u) == 0u) { if (xb_ld(&(bar)[XB_TMO])) break; if (_sp > XB_SPIN_CAP) { atomicAdd(&(bar)[XB_TMO], 1u); break; } } } } while (0)
; __device__ __forceinline__ void xcd_barrier(const XcdBarrier& b) {
;     ...
;         const unsigned old = xb_add(&bar[XB_XSUB(b.x)], 1u);
;         const unsigned gen = old / nloc;
;         if (old + 1u == (gen + 1u) * nloc) {
;             __builtin_amdgcn_fence(__ATOMIC_RELEASE, "agent");
;             asm volatile("s_waitcnt vmcnt(0)" ::: "memory");
;             const unsigned og = xb_add(&bar[XB_TOP], 1u);
;             const unsigned tg = og / nx;
;             if (og + 1u == (tg + 1u) * nx) xb_add(&bar[XB_TOPGEN], 1u);
;             else XB_SPIN(xb_ld(&bar[XB_TOPGEN]) == tg, bar);
;             __builtin_amdgcn_fence(__ATOMIC_ACQUIRE, "agent");
;             xb_add(&bar[XB_XGEN(b.x)], 1u);
;             asm volatile("s_waitcnt vmcnt(0)" ::: "memory");
;         } else {
;             XB_SPIN(xb_ld(&bar[XB_XGEN(b.x)]) == gen, bar);
;             __builtin_amdgcn_fence(__ATOMIC_ACQUIRE, "agent");
;             asm volatile("s_waitcnt vmcnt(0)" ::: "memory");
;         }
.LBB0_343:
	s_or_b64 exec, exec, s[10:11]
	v_cvt_f32_u32_e32 v4, v2
	s_waitcnt vmcnt(0)
	v_readfirstlane_b32 s8, v3
	s_add_u32 s6, s6, 0x2400
	s_addc_u32 s7, s7, 0
	v_rcp_iflag_f32_e32 v4, v4
	v_add_u32_e32 v5, s8, v1
	v_mul_f32_e32 v3, 0x4f7ffffe, v4
	v_cvt_u32_f32_e32 v3, v3
	v_sub_u32_e32 v4, 0, v2
	v_mul_lo_u32 v1, v4, v3
	v_mul_hi_u32 v1, v3, v1
	v_add_u32_e32 v1, v3, v1
	v_mul_hi_u32 v1, v5, v1
	v_mul_lo_u32 v3, v1, v2
	v_sub_u32_e32 v3, v5, v3
	v_add_u32_e32 v4, 1, v1
	v_cmp_ge_u32_e32 vcc, v3, v2
	s_nop 1
	v_cndmask_b32_e32 v1, v1, v4, vcc
	v_sub_u32_e32 v4, v3, v2
	v_cndmask_b32_e32 v3, v3, v4, vcc
	v_add_u32_e32 v4, 1, v1
	v_cmp_ge_u32_e32 vcc, v3, v2
	v_add_u32_e32 v3, 1, v5
	s_nop 0
	v_cndmask_b32_e32 v1, v1, v4, vcc
	v_mul_lo_u32 v4, v2, v1
	v_add_u32_e32 v2, v4, v2
	v_cmp_ne_u32_e32 vcc, v3, v2
	s_and_saveexec_b64 s[8:9], vcc
	s_xor_b64 s[8:9], exec, s[8:9]
	s_cbranch_execz .LBB0_357
	s_waitcnt lgkmcnt(0)
	buffer_inv sc1
	global_load_dword v0, v197, s[6:7] sc1
	s_waitcnt vmcnt(0)
	v_cmp_eq_u32_e32 vcc, v0, v1
	s_and_saveexec_b64 s[10:11], vcc
	s_cbranch_execz .LBB0_356
	s_mov_b32 s22, 1
	s_mov_b64 s[12:13], 0
	s_branch .LBB0_347

; __device__ __forceinline__ unsigned xb_ld(unsigned* p)              { return __hip_atomic_load(p, __ATOMIC_RELAXED, __HIP_MEMORY_SCOPE_AGENT); }
; __device__ __forceinline__ unsigned xb_add(unsigned* p, unsigned v) { return __hip_atomic_fetch_add(p, v, __ATOMIC_RELAXED, __HIP_MEMORY_SCOPE_AGENT); }
; #define XB_SPIN(cond, bar) do { unsigned _sp = 0; while (cond) { __builtin_amdgcn_s_sleep(1); \
;     if ((++_sp & 255u) == 0u) { if (xb_ld(&(bar)[XB_TMO])) break; if (_sp > XB_SPIN_CAP) { atomicAdd(&(bar)[XB_TMO], 1u); break; } } } } while (0)
; __device__ __forceinline__ void xcd_barrier(const XcdBarrier& b) {
;     ...
;         const unsigned old = xb_add(&bar[XB_XSUB(b.x)], 1u);
;         const unsigned gen = old / nloc;
;         if (old + 1u == (gen + 1u) * nloc) {
;             __builtin_amdgcn_fence(__ATOMIC_RELEASE, "agent");
;             asm volatile("s_waitcnt vmcnt(0)" ::: "memory");
;             const unsigned og = xb_add(&bar[XB_TOP], 1u);
;             const unsigned tg = og / nx;
;             if (og + 1u == (tg + 1u) * nx) xb_add(&bar[XB_TOPGEN], 1u);
;             else XB_SPIN(xb_ld(&bar[XB_TOPGEN]) == tg, bar);
;             __builtin_amdgcn_fence(__ATOMIC_ACQUIRE, "agent");
;             xb_add(&bar[XB_XGEN(b.x)], 1u);
;             asm volatile("s_waitcnt vmcnt(0)" ::: "memory");
;         } else {
;             XB_SPIN(xb_ld(&bar[XB_XGEN(b.x)]) == gen, bar);
;             __builtin_amdgcn_fence(__ATOMIC_ACQUIRE, "agent");
;             asm volatile("s_waitcnt vmcnt(0)" ::: "memory");
;         }
.LBB0_847:
	s_or_b64 exec, exec, s[10:11]
	v_cvt_f32_u32_e32 v4, v2
	s_waitcnt vmcnt(0)
	v_readfirstlane_b32 s8, v3
	s_add_u32 s6, s6, 0x2400
	s_addc_u32 s7, s7, 0
	v_rcp_iflag_f32_e32 v4, v4
	v_add_u32_e32 v5, s8, v1
	v_mul_f32_e32 v3, 0x4f7ffffe, v4
	v_cvt_u32_f32_e32 v3, v3
	v_sub_u32_e32 v4, 0, v2
	v_mul_lo_u32 v1, v4, v3
	v_mul_hi_u32 v1, v3, v1
	v_add_u32_e32 v1, v3, v1
	v_mul_hi_u32 v1, v5, v1
	v_mul_lo_u32 v3, v1, v2
	v_sub_u32_e32 v3, v5, v3
	v_add_u32_e32 v4, 1, v1
	v_cmp_ge_u32_e32 vcc, v3, v2
	s_nop 1
	v_cndmask_b32_e32 v1, v1, v4, vcc
	v_sub_u32_e32 v4, v3, v2
	v_cndmask_b32_e32 v3, v3, v4, vcc
	v_add_u32_e32 v4, 1, v1
	v_cmp_ge_u32_e32 vcc, v3, v2
	v_add_u32_e32 v3, 1, v5
	s_nop 0
	v_cndmask_b32_e32 v1, v1, v4, vcc
	v_mul_lo_u32 v4, v2, v1
	v_add_u32_e32 v2, v4, v2
	v_cmp_ne_u32_e32 vcc, v3, v2
	s_and_saveexec_b64 s[8:9], vcc
	s_xor_b64 s[8:9], exec, s[8:9]
	s_cbranch_execz .LBB0_861
	s_waitcnt lgkmcnt(0)
	buffer_inv sc1
	global_load_dword v0, v197, s[6:7] sc1
	s_waitcnt vmcnt(0)
	v_cmp_eq_u32_e32 vcc, v0, v1
	s_and_saveexec_b64 s[10:11], vcc
	s_cbranch_execz .LBB0_860
	s_mov_b32 s23, 1
	s_mov_b64 s[12:13], 0
	s_branch .LBB0_851
